# stack plus GEMM call prologue: second DMA batch (K-tile 1) issued before the first wait, first wait vmcnt(8) (15 prologues)
# speedup vs baseline: 1.0037x; 1.0003x over previous
; #define PG8_STAGE(bufoff, gbase, voff) do { _Pragma("unroll") for (int _i = 0; _i < 2; ++_i) \
;         __builtin_amdgcn_global_load_lds((const unsigned*)((const char*)(gbase) + (voff)[_i]), (PG8_LAS unsigned*)(lds + (bufoff) + ldsw + _i * 8192), 16, 0, 0); } while (0)
; #define PG8_WAIT_V(n) asm volatile("s_waitcnt vmcnt(" #n ")" ::: "memory")
; #define PG8_BAR __builtin_amdgcn_s_barrier()
; template <class Epi, class Sched, bool ALIGN_EPI = false, bool SP2 = false>
; __device__ __forceinline__ void gemm_phase(PG8_LAS unsigned char* lds, const Gemm g, const Sched& S, const Epi& E) {
;     ...
;     const int tid = tid_, wid = __builtin_amdgcn_readfirstlane(tid >> 6), lane = tid & 63, wr = wid >> 2, wc = wid & 3, fr = lane & 15, fq = lane >> 4;
;     const int K = g.K, nt = __builtin_amdgcn_readfirstlane(g.nt);
;     unsigned voffA[2], voffB[2];
; #pragma unroll
;     for (int i = 0; i < 2; ++i) { int R, C; stage_rc(tid * 16 + i * 8192, R, C); const int Rb = Epi::PERM ? ((R & ~31) + perm32(R & 31)) : R;
;         voffA[i] = (unsigned)(R * K + C) * 2u; voffB[i] = (unsigned)(Rb * K + C) * 2u; }
;     const size_t kstep = (size_t)(BK * 2);
;     const size_t hstep = (size_t)HALF * K * 2;
;     const size_t tstep = 2 * hstep;
;     const unsigned ldsw = (unsigned)wid * 1024u;
;     const int aoff = lds_byte(wr * 64 + fr, fq * 8), boff = lds_byte(wc * 32 + fr, fq * 8);
;     ...
;     if constexpr (SP2) {
;         PG8_STAGE(PG8_SB(0, 0), cB, voffB); PG8_STAGE(PG8_SB(0, 1), cB + hstep, voffB); PG8_STAGE(PG8_SA(0, 0), cA, voffA); PG8_STAGE(PG8_SA(0, 1), cA + hstep, voffA);
;         if (wr == 1) PG8_BAR;
;         PG8_WAIT_V(2); PG8_BAR;
;         PG8_STAGE(PG8_SB(1, 0), cB + kstep, voffB); PG8_STAGE(PG8_SA(1, 0), cA + kstep, voffA); PG8_STAGE(PG8_SB(1, 1), cB + hstep + kstep, voffB);
;         PG8_WAIT_V(6); PG8_BAR;
.LBB0_82:
	s_lshl_b32 s10, s10, 5
	s_and_b32 s20, s10, 0x60
	s_mov_b64 s[10:11], 0x80
	s_add_i32 m0, s19, 0x18000
	v_lshl_add_u64 v[8:9], v[8:9], 0, s[10:11]
	s_ashr_i32 s28, s96, 31
	s_lshl_b32 s13, s12, 13
	s_lshl_b32 s21, s20, 7
	global_load_lds_dwordx4 v[8:9], off
	v_lshl_add_u64 v[6:7], v[6:7], 0, s[10:11]
	s_add_i32 m0, s19, 0x1a000
	s_add_i32 s29, s19, 0x8000
	s_add_i32 s30, s19, 0xa000
	global_load_lds_dwordx4 v[6:7], off
	v_lshl_add_u64 v[2:3], v[2:3], 0, s[10:11]
	s_mov_b32 m0, s29
	s_add_u32 s14, s42, 0x80080
	global_load_lds_dwordx4 v[2:3], off
	v_lshl_add_u64 v[2:3], v[4:5], 0, s[10:11]
	s_mov_b32 m0, s30
	s_addc_u32 s15, s43, 0
	global_load_lds_dwordx4 v[2:3], off
	s_add_i32 m0, s19, 0x1c000
	v_lshl_add_u64 v[2:3], s[14:15], 0, v[134:135]
	global_load_lds_dwordx4 v[2:3], off
	v_lshl_add_u64 v[2:3], s[14:15], 0, v[130:131]
	s_add_i32 m0, s19, 0x1e000
	s_cmpk_lt_u32 s7, 0x100
	global_load_lds_dwordx4 v[2:3], off
	s_waitcnt vmcnt(8)
	s_barrier
	v_lshrrev_b32_e32 v3, 1, v11
	v_and_b32_e32 v3, 24, v3
	v_and_b32_e32 v2, 15, v11
	v_lshlrev_b32_e32 v4, 1, v3
	v_lshl_or_b32 v150, s12, 6, v2
	v_lshl_or_b32 v2, v2, 6, v4
	v_lshlrev_b32_e32 v4, 2, v11
	v_and_b32_e32 v4, 32, v4
	v_bitop3_b32 v5, v2, s13, v4 bitop3:0xde
	v_bitop3_b32 v151, v2, s21, v4 bitop3:0xde
	v_lshlrev_b32_e32 v2, 15, v15
	v_and_b32_e32 v2, 0xffff0000, v2
	v_or_b32_e32 v152, s20, v3
	v_lshl_add_u32 v2, v14, 12, v2
	v_and_b32_e32 v3, 1, v15
	v_lshl_or_b32 v2, v3, 6, v2
	v_lshl_add_u32 v138, v16, 1, v2
	v_lshlrev_b32_e32 v2, 15, v10
	v_and_b32_e32 v2, 0xffff0000, v2
	s_waitcnt vmcnt(6)
	v_lshl_add_u32 v2, v12, 12, v2
	v_and_b32_e32 v3, 1, v10
	s_cselect_b64 s[12:13], -1, 0
	v_lshl_or_b32 v2, v3, 6, v2
	s_add_i32 s31, 0, 0x10000
	s_add_i32 s39, 0, 0x14000
	s_sext_i32_i16 s47, s6
	v_mov_b32_e32 v139, v135
	v_lshl_add_u32 v140, v13, 1, v2
	v_mov_b32_e32 v141, v135
	v_mov_b64_e32 v[142:143], 0x5d8
	v_mov_b64_e32 v[144:145], 0x5d7
	v_add_u32_e32 v153, s31, v151
	v_add_u32_e32 v154, s39, v151
	v_add_u32_e32 v155, 0, v5
	s_movk_i32 s46, 0x2c00
	s_barrier
	s_branch .LBB0_85

; #define PG8_STAGE(bufoff, gbase, voff) do { _Pragma("unroll") for (int _i = 0; _i < 2; ++_i) \
;         __builtin_amdgcn_global_load_lds((const unsigned*)((const char*)(gbase) + (voff)[_i]), (PG8_LAS unsigned*)(lds + (bufoff) + ldsw + _i * 8192), 16, 0, 0); } while (0)
; #define PG8_WAIT_V(n) asm volatile("s_waitcnt vmcnt(" #n ")" ::: "memory")
; #define PG8_BAR __builtin_amdgcn_s_barrier()
; template <class Epi, class Sched, bool ALIGN_EPI = false, bool SP2 = false>
; __device__ __forceinline__ void gemm_phase(PG8_LAS unsigned char* lds, const Gemm g, const Sched& S, const Epi& E) {
;     ...
;     const int tid = tid_, wid = __builtin_amdgcn_readfirstlane(tid >> 6), lane = tid & 63, wr = wid >> 2, wc = wid & 3, fr = lane & 15, fq = lane >> 4;
;     const int K = g.K, nt = __builtin_amdgcn_readfirstlane(g.nt);
;     unsigned voffA[2], voffB[2];
; #pragma unroll
;     for (int i = 0; i < 2; ++i) { int R, C; stage_rc(tid * 16 + i * 8192, R, C); const int Rb = Epi::PERM ? ((R & ~31) + perm32(R & 31)) : R;
;         voffA[i] = (unsigned)(R * K + C) * 2u; voffB[i] = (unsigned)(Rb * K + C) * 2u; }
;     const size_t kstep = (size_t)(BK * 2);
;     const size_t hstep = (size_t)HALF * K * 2;
;     const size_t tstep = 2 * hstep;
;     const unsigned ldsw = (unsigned)wid * 1024u;
;     const int aoff = lds_byte(wr * 64 + fr, fq * 8), boff = lds_byte(wc * 32 + fr, fq * 8);
;     ...
;     if constexpr (SP2) {
;         PG8_STAGE(PG8_SB(0, 0), cB, voffB); PG8_STAGE(PG8_SB(0, 1), cB + hstep, voffB); PG8_STAGE(PG8_SA(0, 0), cA, voffA); PG8_STAGE(PG8_SA(0, 1), cA + hstep, voffA);
;         if (wr == 1) PG8_BAR;
;         PG8_WAIT_V(2); PG8_BAR;
;         PG8_STAGE(PG8_SB(1, 0), cB + kstep, voffB); PG8_STAGE(PG8_SA(1, 0), cA + kstep, voffA); PG8_STAGE(PG8_SB(1, 1), cB + hstep + kstep, voffB);
;         PG8_WAIT_V(6); PG8_BAR;
.LBB0_159:
	s_lshl_b32 s9, s9, 5
	s_mov_b64 s[12:13], 0x80
	s_and_b32 s21, s9, 0x60
	s_add_i32 m0, s18, 0x18000
	v_lshl_add_u64 v[8:9], v[8:9], 0, s[12:13]
	s_ashr_i32 s27, s96, 31
	s_lshl_b32 s15, s8, 13
	s_lshl_b32 s9, s21, 7
	global_load_lds_dwordx4 v[8:9], off
	v_lshl_add_u64 v[4:5], v[4:5], 0, s[12:13]
	s_add_i32 m0, s18, 0x1a000
	s_add_i32 s28, s18, 0x8000
	s_add_i32 s29, s18, 0xa000
	global_load_lds_dwordx4 v[4:5], off
	v_lshl_add_u64 v[2:3], v[2:3], 0, s[12:13]
	s_mov_b32 m0, s28
	s_add_u32 s30, s36, 0x160080
	global_load_lds_dwordx4 v[2:3], off
	v_lshl_add_u64 v[2:3], v[6:7], 0, s[12:13]
	s_mov_b32 m0, s29
	s_addc_u32 s31, s37, 0
	global_load_lds_dwordx4 v[2:3], off
	s_add_i32 m0, s18, 0x1c000
	v_lshl_add_u64 v[2:3], s[30:31], 0, v[134:135]
	global_load_lds_dwordx4 v[2:3], off
	v_lshl_add_u64 v[2:3], s[30:31], 0, v[130:131]
	s_add_i32 m0, s18, 0x1e000
	s_cmpk_lt_u32 s6, 0x100
	global_load_lds_dwordx4 v[2:3], off
	s_waitcnt vmcnt(8)
	s_barrier
	v_lshrrev_b32_e32 v3, 1, v14
	v_and_b32_e32 v3, 24, v3
	v_and_b32_e32 v2, 15, v14
	v_lshlrev_b32_e32 v4, 1, v3
	v_lshl_or_b32 v148, s8, 6, v2
	v_lshl_or_b32 v2, v2, 6, v4
	v_lshlrev_b32_e32 v4, 2, v14
	v_and_b32_e32 v4, 32, v4
	v_bitop3_b32 v5, v2, s15, v4 bitop3:0xde
	v_bitop3_b32 v149, v2, s9, v4 bitop3:0xde
	v_or_b32_e32 v150, s21, v3
	v_lshrrev_b32_e32 v3, 1, v16
	v_mul_lo_u32 v2, v15, s7
	v_mad_u64_u32 v[2:3], s[30:31], v3, s20, v[2:3]
	v_or_b32_e32 v2, v2, v17
	s_mov_b64 s[8:9], 0x160080
	v_add_lshl_u32 v2, v2, v18, 1
	v_mov_b32_e32 v3, v135
	v_lshl_add_u64 v[138:139], v[2:3], 0, s[8:9]
	v_lshrrev_b32_e32 v3, 1, v10
	v_mul_lo_u32 v2, v11, s7
	v_mad_u64_u32 v[2:3], s[6:7], v3, s20, v[2:3]
	s_waitcnt vmcnt(6)
	v_or_b32_e32 v2, v2, v12
	s_sext_i32_i8 s45, s14
	s_cselect_b64 s[14:15], -1, 0
	v_add_lshl_u32 v2, v2, v13, 1
	v_mov_b32_e32 v3, v135
	s_add_i32 s30, 0, 0x10000
	s_add_i32 s31, 0, 0x14000
	v_lshl_add_u64 v[140:141], v[2:3], 0, s[8:9]
	v_mov_b64_e32 v[142:143], 0x100
	v_mov_b64_e32 v[144:145], 0xff
	v_add_u32_e32 v151, s30, v149
	v_add_u32_e32 v152, s31, v149
	v_add_u32_e32 v153, 0, v5
	s_barrier
	s_branch .LBB0_162

; #define PG8_STAGE(bufoff, gbase, voff) do { _Pragma("unroll") for (int _i = 0; _i < 2; ++_i) \
;         __builtin_amdgcn_global_load_lds((const unsigned*)((const char*)(gbase) + (voff)[_i]), (PG8_LAS unsigned*)(lds + (bufoff) + ldsw + _i * 8192), 16, 0, 0); } while (0)
; #define PG8_WAIT_V(n) asm volatile("s_waitcnt vmcnt(" #n ")" ::: "memory")
; #define PG8_BAR __builtin_amdgcn_s_barrier()
; template <class Epi, class Sched, bool ALIGN_EPI = false, bool SP2 = false>
; __device__ __forceinline__ void gemm_phase(PG8_LAS unsigned char* lds, const Gemm g, const Sched& S, const Epi& E) {
;     ...
;     const int tid = tid_, wid = __builtin_amdgcn_readfirstlane(tid >> 6), lane = tid & 63, wr = wid >> 2, wc = wid & 3, fr = lane & 15, fq = lane >> 4;
;     const int K = g.K, nt = __builtin_amdgcn_readfirstlane(g.nt);
;     unsigned voffA[2], voffB[2];
; #pragma unroll
;     for (int i = 0; i < 2; ++i) { int R, C; stage_rc(tid * 16 + i * 8192, R, C); const int Rb = Epi::PERM ? ((R & ~31) + perm32(R & 31)) : R;
;         voffA[i] = (unsigned)(R * K + C) * 2u; voffB[i] = (unsigned)(Rb * K + C) * 2u; }
;     const size_t kstep = (size_t)(BK * 2);
;     const size_t hstep = (size_t)HALF * K * 2;
;     const size_t tstep = 2 * hstep;
;     const unsigned ldsw = (unsigned)wid * 1024u;
;     const int aoff = lds_byte(wr * 64 + fr, fq * 8), boff = lds_byte(wc * 32 + fr, fq * 8);
;     ...
;     if constexpr (SP2) {
;         PG8_STAGE(PG8_SB(0, 0), cB, voffB); PG8_STAGE(PG8_SB(0, 1), cB + hstep, voffB); PG8_STAGE(PG8_SA(0, 0), cA, voffA); PG8_STAGE(PG8_SA(0, 1), cA + hstep, voffA);
;         if (wr == 1) PG8_BAR;
;         PG8_WAIT_V(2); PG8_BAR;
;         PG8_STAGE(PG8_SB(1, 0), cB + kstep, voffB); PG8_STAGE(PG8_SA(1, 0), cA + kstep, voffA); PG8_STAGE(PG8_SB(1, 1), cB + hstep + kstep, voffB);
;         PG8_WAIT_V(6); PG8_BAR;
.LBB0_183:
	s_lshl_b32 s14, s14, 5
	s_and_b32 s36, s14, 0x60
	s_lshl_b32 s21, s20, 13
	s_lshl_b32 s31, s36, 7
	s_add_u32 s27, s34, 0x3ab00000
	s_addc_u32 s28, s35, 0
	s_add_u32 s22, s40, 0x160080
	s_mov_b64 s[14:15], 0x80
	s_addc_u32 s23, s41, 0
	s_add_i32 m0, s19, 0x18000
	v_lshl_add_u64 v[8:9], v[8:9], 0, s[14:15]
	global_load_lds_dwordx4 v[8:9], off
	v_lshl_add_u64 v[6:7], v[6:7], 0, s[14:15]
	s_add_i32 m0, s19, 0x1a000
	s_add_i32 s29, s19, 0x8000
	global_load_lds_dwordx4 v[6:7], off
	v_lshl_add_u64 v[2:3], v[2:3], 0, s[14:15]
	s_mov_b32 m0, s29
	s_add_i32 s30, s19, 0xa000
	global_load_lds_dwordx4 v[2:3], off
	v_lshl_add_u64 v[2:3], v[4:5], 0, s[14:15]
	s_mov_b32 m0, s30
	s_mov_b32 s50, s17
	global_load_lds_dwordx4 v[2:3], off
	s_add_i32 m0, s19, 0x1c000
	v_lshl_add_u64 v[2:3], s[22:23], 0, v[132:133]
	global_load_lds_dwordx4 v[2:3], off
	v_lshl_add_u64 v[2:3], s[22:23], 0, v[130:131]
	s_add_i32 m0, s19, 0x1e000
	s_mov_b64 s[22:23], 0x160080
	global_load_lds_dwordx4 v[2:3], off
	s_waitcnt vmcnt(8)
	s_barrier
	v_bfe_u32 v2, v10, 4, 2
	v_and_b32_e32 v3, 15, v10
	v_lshlrev_b32_e32 v5, 4, v2
	v_lshl_or_b32 v4, s20, 6, v3
	v_lshl_or_b32 v3, v3, 6, v5
	v_lshlrev_b32_e32 v5, 2, v10
	v_and_b32_e32 v5, 32, v5
	v_bitop3_b32 v6, v3, s21, v5 bitop3:0xde
	v_bitop3_b32 v138, v3, s31, v5 bitop3:0xde
	v_lshl_or_b32 v140, v2, 2, s36
	v_lshrrev_b32_e32 v3, 1, v16
	v_mul_lo_u32 v2, v15, s7
	v_mad_u64_u32 v[2:3], s[36:37], v3, s11, v[2:3]
	v_or_b32_e32 v2, v2, v17
	v_add_lshl_u32 v2, v2, v18, 1
	v_mov_b32_e32 v3, v133
	v_lshl_add_u64 v[134:135], v[2:3], 0, s[22:23]
	v_lshrrev_b32_e32 v3, 1, v11
	v_mul_lo_u32 v2, v12, s7
	s_cmpk_lt_u32 s6, 0x100
	v_mad_u64_u32 v[2:3], s[6:7], v3, s11, v[2:3]
	s_waitcnt vmcnt(6)
	v_or_b32_e32 v2, v2, v13
	s_cselect_b64 s[20:21], -1, 0
	v_add_lshl_u32 v2, v2, v14, 1
	v_mov_b32_e32 v3, v133
	s_add_i32 s46, 0, 0x10000
	s_add_i32 s47, 0, 0x14000
	s_mov_b32 s31, 0
	v_add_u32_e32 v139, 0xffffe000, v4
	v_lshl_add_u64 v[136:137], v[2:3], 0, s[22:23]
	v_add_u32_e32 v141, s46, v138
	v_add_u32_e32 v142, s47, v138
	v_add_u32_e32 v143, 0, v6
	s_mov_b32 s51, s18
	s_barrier
	s_branch .LBB0_186

; #define PG8_STAGE(bufoff, gbase, voff) do { _Pragma("unroll") for (int _i = 0; _i < 2; ++_i) \
;         __builtin_amdgcn_global_load_lds((const unsigned*)((const char*)(gbase) + (voff)[_i]), (PG8_LAS unsigned*)(lds + (bufoff) + ldsw + _i * 8192), 16, 0, 0); } while (0)
; #define PG8_WAIT_V(n) asm volatile("s_waitcnt vmcnt(" #n ")" ::: "memory")
; #define PG8_BAR __builtin_amdgcn_s_barrier()
; template <class Epi, class Sched, bool ALIGN_EPI = false, bool SP2 = false>
; __device__ __forceinline__ void gemm_phase(PG8_LAS unsigned char* lds, const Gemm g, const Sched& S, const Epi& E) {
;     ...
;     const int tid = tid_, wid = __builtin_amdgcn_readfirstlane(tid >> 6), lane = tid & 63, wr = wid >> 2, wc = wid & 3, fr = lane & 15, fq = lane >> 4;
;     const int K = g.K, nt = __builtin_amdgcn_readfirstlane(g.nt);
;     unsigned voffA[2], voffB[2];
; #pragma unroll
;     for (int i = 0; i < 2; ++i) { int R, C; stage_rc(tid * 16 + i * 8192, R, C); const int Rb = Epi::PERM ? ((R & ~31) + perm32(R & 31)) : R;
;         voffA[i] = (unsigned)(R * K + C) * 2u; voffB[i] = (unsigned)(Rb * K + C) * 2u; }
;     const size_t kstep = (size_t)(BK * 2);
;     const size_t hstep = (size_t)HALF * K * 2;
;     const size_t tstep = 2 * hstep;
;     const unsigned ldsw = (unsigned)wid * 1024u;
;     const int aoff = lds_byte(wr * 64 + fr, fq * 8), boff = lds_byte(wc * 32 + fr, fq * 8);
;     ...
;     if constexpr (SP2) {
;         PG8_STAGE(PG8_SB(0, 0), cB, voffB); PG8_STAGE(PG8_SB(0, 1), cB + hstep, voffB); PG8_STAGE(PG8_SA(0, 0), cA, voffA); PG8_STAGE(PG8_SA(0, 1), cA + hstep, voffA);
;         if (wr == 1) PG8_BAR;
;         PG8_WAIT_V(2); PG8_BAR;
;         PG8_STAGE(PG8_SB(1, 0), cB + kstep, voffB); PG8_STAGE(PG8_SA(1, 0), cA + kstep, voffA); PG8_STAGE(PG8_SB(1, 1), cB + hstep + kstep, voffB);
;         PG8_WAIT_V(6); PG8_BAR;
.LBB0_334:
	s_add_u32 s84, s34, 0x1ed00000
	s_addc_u32 s97, s35, 0
	s_add_u32 s74, s34, 0x2fe00000
	s_addc_u32 s75, s35, 0
	s_add_u32 s76, s90, 0x4400000
	s_addc_u32 s77, s91, 0
	s_add_u32 s78, s90, 0x4c1c040
	v_bfe_u32 v19, v10, 4, 2
	s_addc_u32 s79, s91, 0
	v_and_b32_e32 v18, 15, v10
	v_lshlrev_b32_e32 v21, 4, v19
	s_add_u32 s86, s34, 0x2fd00000
	v_lshl_or_b32 v141, s0, 6, v18
	v_lshl_or_b32 v18, v18, 6, v21
	v_lshlrev_b32_e32 v21, 2, v10
	s_mov_b64 s[90:91], 0x80
	s_addc_u32 s87, s35, 0
	s_and_b32 s5, s4, 3
	s_lshl_b32 s0, s0, 13
	v_and_b32_e32 v21, 32, v21
	s_add_i32 m0, s59, 0x18000
	v_lshl_add_u64 v[8:9], v[8:9], 0, s[90:91]
	s_ashr_i32 s72, s96, 31
	s_ashr_i32 s73, s2, 31
	v_bitop3_b32 v22, v18, s0, v21 bitop3:0xde
	s_lshl_b32 s0, s5, 12
	global_load_lds_dwordx4 v[8:9], off
	v_lshl_add_u64 v[6:7], v[6:7], 0, s[90:91]
	s_add_i32 m0, s59, 0x1a000
	s_add_i32 s92, s59, 0x8000
	s_add_i32 s93, s59, 0xa000
	v_bitop3_b32 v172, v18, s0, v21 bitop3:0xde
	global_load_lds_dwordx4 v[6:7], off
	v_lshl_add_u64 v[2:3], v[2:3], 0, s[90:91]
	s_mov_b32 m0, s92
	s_add_u32 s0, s14, 0x80080
	global_load_lds_dwordx4 v[2:3], off
	v_lshl_add_u64 v[2:3], v[4:5], 0, s[90:91]
	s_mov_b32 m0, s93
	s_addc_u32 s1, s15, 0
	global_load_lds_dwordx4 v[2:3], off
	s_add_i32 m0, s59, 0x1c000
	v_lshl_add_u64 v[2:3], s[0:1], 0, v[132:133]
	global_load_lds_dwordx4 v[2:3], off
	v_lshl_add_u64 v[2:3], s[0:1], 0, v[136:137]
	s_add_i32 m0, s59, 0x1e000
	s_cmpk_lt_u32 s3, 0x100
	global_load_lds_dwordx4 v[2:3], off
	s_waitcnt vmcnt(8)
	s_barrier
	s_cselect_b64 s[0:1], -1, 0
	v_lshrrev_b32_e32 v17, 4, v10
	v_writelane_b32 v244, s0, 18
	v_and_b32_e32 v2, 3, v10
	v_lshlrev_b32_e32 v20, 3, v19
	v_writelane_b32 v244, s1, 19
	v_subrev_co_u32_e64 v140, s[0:1], 1, v2
	v_bitop3_b32 v2, s4, v17, 3 bitop3:0xa8
	v_lshl_or_b32 v173, s5, 5, v20
	s_lshl_b32 s3, s5, 3
	v_cmp_eq_u32_e64 s[4:5], 0, v2
	v_lshlrev_b32_e32 v2, 15, v11
	v_and_b32_e32 v2, 0xffff0000, v2
	v_lshl_add_u32 v2, v12, 12, v2
	v_and_b32_e32 v3, 1, v11
	v_lshl_or_b32 v2, v3, 6, v2
	v_lshl_add_u32 v142, v13, 1, v2
	v_lshlrev_b32_e32 v2, 15, v14
	v_and_b32_e32 v2, 0xffff0000, v2
	v_lshl_add_u32 v2, v15, 12, v2
	v_and_b32_e32 v3, 1, v14
	s_waitcnt vmcnt(6)
	v_writelane_b32 v244, s3, 20
	v_lshl_or_b32 v2, v3, 6, v2
	v_writelane_b32 v244, s4, 22
	v_lshl_add_u32 v144, v16, 1, v2
	s_add_i32 s95, 0, 0x10000
	s_add_i32 s81, 0, 0x14000
	v_mbcnt_lo_u32_b32 v2, -1, 0
	v_cmp_eq_u32_e64 s[20:21], 0, v19
	v_writelane_b32 v244, s5, 23
	v_or_b32_e32 v174, 16, v141
	v_or_b32_e32 v175, 32, v141
	v_or_b32_e32 v176, 48, v141
	v_mov_b32_e32 v143, v139
	v_mov_b32_e32 v145, v139
	v_mov_b64_e32 v[146:147], 0x792
	v_mov_b64_e32 v[148:149], 0x791
	v_add_u32_e32 v177, s95, v172
	v_add_u32_e32 v178, s81, v172
	v_add_u32_e32 v179, 0, v22
	s_mov_b32 s52, 0x3e6d3388
	s_mov_b32 s54, 0x3f07dc22
	s_mov_b32 s58, 0x3f35f0e3
	s_mov_b32 s60, 0xbe11a98e
	s_mov_b32 s62, 0x3e027906
	s_mov_b32 s64, 0xbf38aa3b
	s_mov_b32 s85, 0xbfb8aa3b
	s_mov_b32 s3, 0x800000
	s_mov_b32 s4, 0x3f317217
	s_mov_b32 s5, 0x7f800000
	v_mbcnt_hi_u32_b32 v180, -1, v2
	v_mov_b32_e32 v181, 0x41b17218
	s_mov_b32 s94, 0
	s_barrier
	s_branch .LBB0_337

; #define PG8_STAGE(bufoff, gbase, voff) do { _Pragma("unroll") for (int _i = 0; _i < 2; ++_i) \
;         __builtin_amdgcn_global_load_lds((const unsigned*)((const char*)(gbase) + (voff)[_i]), (PG8_LAS unsigned*)(lds + (bufoff) + ldsw + _i * 8192), 16, 0, 0); } while (0)
; #define PG8_WAIT_V(n) asm volatile("s_waitcnt vmcnt(" #n ")" ::: "memory")
; #define PG8_BAR __builtin_amdgcn_s_barrier()
; template <class Epi, class Sched, bool ALIGN_EPI = false, bool SP2 = false>
; __device__ __forceinline__ void gemm_phase(PG8_LAS unsigned char* lds, const Gemm g, const Sched& S, const Epi& E) {
;     ...
;     const int tid = tid_, wid = __builtin_amdgcn_readfirstlane(tid >> 6), lane = tid & 63, wr = wid >> 2, wc = wid & 3, fr = lane & 15, fq = lane >> 4;
;     const int K = g.K, nt = __builtin_amdgcn_readfirstlane(g.nt);
;     unsigned voffA[2], voffB[2];
; #pragma unroll
;     for (int i = 0; i < 2; ++i) { int R, C; stage_rc(tid * 16 + i * 8192, R, C); const int Rb = Epi::PERM ? ((R & ~31) + perm32(R & 31)) : R;
;         voffA[i] = (unsigned)(R * K + C) * 2u; voffB[i] = (unsigned)(Rb * K + C) * 2u; }
;     const size_t kstep = (size_t)(BK * 2);
;     const size_t hstep = (size_t)HALF * K * 2;
;     const size_t tstep = 2 * hstep;
;     const unsigned ldsw = (unsigned)wid * 1024u;
;     const int aoff = lds_byte(wr * 64 + fr, fq * 8), boff = lds_byte(wc * 32 + fr, fq * 8);
;     ...
;     if constexpr (SP2) {
;         PG8_STAGE(PG8_SB(0, 0), cB, voffB); PG8_STAGE(PG8_SB(0, 1), cB + hstep, voffB); PG8_STAGE(PG8_SA(0, 0), cA, voffA); PG8_STAGE(PG8_SA(0, 1), cA + hstep, voffA);
;         if (wr == 1) PG8_BAR;
;         PG8_WAIT_V(2); PG8_BAR;
;         PG8_STAGE(PG8_SB(1, 0), cB + kstep, voffB); PG8_STAGE(PG8_SA(1, 0), cA + kstep, voffA); PG8_STAGE(PG8_SB(1, 1), cB + hstep + kstep, voffB);
;         PG8_WAIT_V(6); PG8_BAR;
.LBB0_1189:
	s_add_u32 s12, s34, 0x38900000
	s_addc_u32 s13, s35, 0
	s_lshl_b32 s14, s14, 5
	s_and_b32 s20, s14, 0x60
	s_mov_b64 s[14:15], 0x80
	s_add_i32 m0, s27, 0x18000
	v_lshl_add_u64 v[8:9], v[8:9], 0, s[14:15]
	s_ashr_i32 s50, s96, 31
	s_lshl_b32 s17, s16, 13
	s_lshl_b32 s21, s20, 7
	global_load_lds_dwordx4 v[8:9], off
	v_lshl_add_u64 v[6:7], v[6:7], 0, s[14:15]
	s_add_i32 m0, s27, 0x1a000
	s_add_i32 s51, s27, 0x8000
	s_add_i32 s52, s27, 0xa000
	global_load_lds_dwordx4 v[6:7], off
	v_lshl_add_u64 v[2:3], v[2:3], 0, s[14:15]
	s_mov_b32 m0, s51
	s_add_u32 s18, s30, 0x100080
	global_load_lds_dwordx4 v[2:3], off
	v_lshl_add_u64 v[2:3], v[4:5], 0, s[14:15]
	s_mov_b32 m0, s52
	s_addc_u32 s19, s31, 0
	global_load_lds_dwordx4 v[2:3], off
	s_add_i32 m0, s27, 0x1c000
	v_lshl_add_u64 v[2:3], s[18:19], 0, v[142:143]
	global_load_lds_dwordx4 v[2:3], off
	v_lshl_add_u64 v[2:3], s[18:19], 0, v[138:139]
	s_add_i32 m0, s27, 0x1e000
	s_sext_i32_i8 s36, s0
	global_load_lds_dwordx4 v[2:3], off
	s_waitcnt vmcnt(8)
	s_barrier
	v_lshrrev_b32_e32 v3, 1, v12
	v_and_b32_e32 v3, 24, v3
	v_and_b32_e32 v2, 15, v12
	v_lshlrev_b32_e32 v4, 1, v3
	v_lshl_or_b32 v160, s16, 6, v2
	v_lshl_or_b32 v4, v2, 6, v4
	v_lshl_or_b32 v162, v2, 11, v3
	v_lshlrev_b32_e32 v2, 16, v15
	v_and_b32_e32 v2, 0xfffe0000, v2
	v_or_b32_e32 v163, s20, v3
	v_lshl_add_u32 v2, v14, 13, v2
	v_and_b32_e32 v3, 1, v15
	v_lshl_or_b32 v2, v3, 6, v2
	v_lshl_add_u32 v146, v16, 1, v2
	v_lshlrev_b32_e32 v2, 16, v10
	v_and_b32_e32 v2, 0xfffe0000, v2
	v_lshlrev_b32_e32 v5, 2, v12
	s_lshl_b32 s0, s16, 17
	v_lshl_add_u32 v2, v11, 13, v2
	v_and_b32_e32 v3, 1, v10
	v_and_b32_e32 v5, 32, v5
	s_mov_b64 s[18:19], 0x100080
	s_waitcnt vmcnt(6)
	s_or_b32 s53, s20, s0
	v_lshl_or_b32 v2, v3, 6, v2
	v_bitop3_b32 v6, v4, s17, v5 bitop3:0xde
	s_cmpk_lt_u32 s1, 0x100
	v_lshl_add_u64 v[148:149], v[146:147], 0, s[18:19]
	v_lshl_add_u32 v146, v13, 1, v2
	v_bitop3_b32 v161, v4, s21, v5 bitop3:0xde
	s_cselect_b64 s[16:17], -1, 0
	v_lshl_add_u64 v[150:151], v[146:147], 0, s[18:19]
	v_mov_b64_e32 v[152:153], 0x100
	v_mov_b64_e32 v[154:155], 0xff
	s_add_i32 s54, 0, 0x14000
	v_add_u32_e32 v164, 0, v6
	s_barrier
	s_branch .LBB0_1192

; #define PG8_STAGE(bufoff, gbase, voff) do { _Pragma("unroll") for (int _i = 0; _i < 2; ++_i) \
;         __builtin_amdgcn_global_load_lds((const unsigned*)((const char*)(gbase) + (voff)[_i]), (PG8_LAS unsigned*)(lds + (bufoff) + ldsw + _i * 8192), 16, 0, 0); } while (0)
; #define PG8_WAIT_V(n) asm volatile("s_waitcnt vmcnt(" #n ")" ::: "memory")
; #define PG8_BAR __builtin_amdgcn_s_barrier()
; template <class Epi, class Sched, bool ALIGN_EPI = false, bool SP2 = false>
; __device__ __forceinline__ void gemm_phase(PG8_LAS unsigned char* lds, const Gemm g, const Sched& S, const Epi& E) {
;     ...
;     const int tid = tid_, wid = __builtin_amdgcn_readfirstlane(tid >> 6), lane = tid & 63, wr = wid >> 2, wc = wid & 3, fr = lane & 15, fq = lane >> 4;
;     const int K = g.K, nt = __builtin_amdgcn_readfirstlane(g.nt);
;     unsigned voffA[2], voffB[2];
; #pragma unroll
;     for (int i = 0; i < 2; ++i) { int R, C; stage_rc(tid * 16 + i * 8192, R, C); const int Rb = Epi::PERM ? ((R & ~31) + perm32(R & 31)) : R;
;         voffA[i] = (unsigned)(R * K + C) * 2u; voffB[i] = (unsigned)(Rb * K + C) * 2u; }
;     const size_t kstep = (size_t)(BK * 2);
;     const size_t hstep = (size_t)HALF * K * 2;
;     const size_t tstep = 2 * hstep;
;     const unsigned ldsw = (unsigned)wid * 1024u;
;     const int aoff = lds_byte(wr * 64 + fr, fq * 8), boff = lds_byte(wc * 32 + fr, fq * 8);
;     ...
;     if constexpr (SP2) {
;         PG8_STAGE(PG8_SB(0, 0), cB, voffB); PG8_STAGE(PG8_SB(0, 1), cB + hstep, voffB); PG8_STAGE(PG8_SA(0, 0), cA, voffA); PG8_STAGE(PG8_SA(0, 1), cA + hstep, voffA);
;         if (wr == 1) PG8_BAR;
;         PG8_WAIT_V(2); PG8_BAR;
;         PG8_STAGE(PG8_SB(1, 0), cB + kstep, voffB); PG8_STAGE(PG8_SA(1, 0), cA + kstep, voffA); PG8_STAGE(PG8_SB(1, 1), cB + hstep + kstep, voffB);
;         PG8_WAIT_V(6); PG8_BAR;
.LBB0_1211:
	s_lshl_b32 s16, s16, 5
	s_and_b32 s22, s16, 0x60
	s_lshl_b32 s11, s19, 13
	s_lshl_b32 s23, s22, 7
	s_add_u32 s49, s34, 0x3ab00000
	s_addc_u32 s50, s35, 0
	s_add_u32 s20, s36, 0x100080
	s_mov_b64 s[16:17], 0x80
	s_addc_u32 s21, s37, 0
	s_add_i32 m0, s45, 0x18000
	v_lshl_add_u64 v[8:9], v[8:9], 0, s[16:17]
	global_load_lds_dwordx4 v[8:9], off
	v_lshl_add_u64 v[6:7], v[6:7], 0, s[16:17]
	s_add_i32 m0, s45, 0x1a000
	s_add_i32 s51, s45, 0x8000
	global_load_lds_dwordx4 v[6:7], off
	v_lshl_add_u64 v[2:3], v[2:3], 0, s[16:17]
	s_mov_b32 m0, s51
	s_add_i32 s52, s45, 0xa000
	global_load_lds_dwordx4 v[2:3], off
	v_lshl_add_u64 v[2:3], v[4:5], 0, s[16:17]
	s_mov_b32 m0, s52
	s_mov_b32 s53, 0
	global_load_lds_dwordx4 v[2:3], off
	s_add_i32 m0, s45, 0x1c000
	v_lshl_add_u64 v[2:3], s[20:21], 0, v[132:133]
	global_load_lds_dwordx4 v[2:3], off
	v_lshl_add_u64 v[2:3], s[20:21], 0, v[130:131]
	s_add_i32 m0, s45, 0x1e000
	s_cmpk_lt_u32 s18, 0x100
	global_load_lds_dwordx4 v[2:3], off
	s_waitcnt vmcnt(8)
	s_barrier
	v_bfe_u32 v3, v10, 4, 2
	v_and_b32_e32 v2, 15, v10
	v_lshlrev_b32_e32 v5, 4, v3
	v_lshl_or_b32 v4, s19, 6, v2
	v_lshl_or_b32 v2, v2, 6, v5
	v_lshlrev_b32_e32 v5, 2, v10
	v_and_b32_e32 v5, 32, v5
	v_bitop3_b32 v6, v2, s11, v5 bitop3:0xde
	v_bitop3_b32 v144, v2, s23, v5 bitop3:0xde
	v_lshlrev_b32_e32 v2, 16, v14
	v_and_b32_e32 v2, 0xfffe0000, v2
	v_lshl_or_b32 v146, v3, 2, s22
	v_lshl_add_u32 v2, v15, 13, v2
	v_and_b32_e32 v3, 1, v14
	v_lshl_or_b32 v2, v3, 6, v2
	v_lshl_add_u32 v134, v16, 1, v2
	v_lshlrev_b32_e32 v2, 16, v11
	v_and_b32_e32 v2, 0xfffe0000, v2
	s_waitcnt vmcnt(6)
	v_lshl_add_u32 v2, v12, 13, v2
	v_and_b32_e32 v3, 1, v11
	s_cselect_b64 s[18:19], -1, 0
	v_lshl_or_b32 v2, v3, 6, v2
	s_add_i32 s54, 0, 0x10000
	s_add_i32 s55, 0, 0x14000
	v_add_u32_e32 v145, 0xffffe000, v4
	v_mov_b32_e32 v135, v133
	v_lshl_add_u32 v136, v13, 1, v2
	v_mov_b32_e32 v137, v133
	v_add_u32_e32 v147, s54, v144
	v_add_u32_e32 v148, s55, v144
	v_add_u32_e32 v149, 0, v6
	s_mov_b32 s56, s43
	s_mov_b32 s57, s44
	s_barrier
	s_branch .LBB0_1214

; #define PG8_STAGE(bufoff, gbase, voff) do { _Pragma("unroll") for (int _i = 0; _i < 2; ++_i) \
;         __builtin_amdgcn_global_load_lds((const unsigned*)((const char*)(gbase) + (voff)[_i]), (PG8_LAS unsigned*)(lds + (bufoff) + ldsw + _i * 8192), 16, 0, 0); } while (0)
; #define PG8_WAIT_V(n) asm volatile("s_waitcnt vmcnt(" #n ")" ::: "memory")
; #define PG8_BAR __builtin_amdgcn_s_barrier()
; template <class Epi, class Sched, bool ALIGN_EPI = false, bool SP2 = false>
; __device__ __forceinline__ void gemm_phase(PG8_LAS unsigned char* lds, const Gemm g, const Sched& S, const Epi& E) {
;     ...
;     const int tid = tid_, wid = __builtin_amdgcn_readfirstlane(tid >> 6), lane = tid & 63, wr = wid >> 2, wc = wid & 3, fr = lane & 15, fq = lane >> 4;
;     const int K = g.K, nt = __builtin_amdgcn_readfirstlane(g.nt);
;     unsigned voffA[2], voffB[2];
; #pragma unroll
;     for (int i = 0; i < 2; ++i) { int R, C; stage_rc(tid * 16 + i * 8192, R, C); const int Rb = Epi::PERM ? ((R & ~31) + perm32(R & 31)) : R;
;         voffA[i] = (unsigned)(R * K + C) * 2u; voffB[i] = (unsigned)(Rb * K + C) * 2u; }
;     const size_t kstep = (size_t)(BK * 2);
;     const size_t hstep = (size_t)HALF * K * 2;
;     const size_t tstep = 2 * hstep;
;     const unsigned ldsw = (unsigned)wid * 1024u;
;     const int aoff = lds_byte(wr * 64 + fr, fq * 8), boff = lds_byte(wc * 32 + fr, fq * 8);
;     ...
;     if constexpr (SP2) {
;         PG8_STAGE(PG8_SB(0, 0), cB, voffB); PG8_STAGE(PG8_SB(0, 1), cB + hstep, voffB); PG8_STAGE(PG8_SA(0, 0), cA, voffA); PG8_STAGE(PG8_SA(0, 1), cA + hstep, voffA);
;         if (wr == 1) PG8_BAR;
;         PG8_WAIT_V(2); PG8_BAR;
;         PG8_STAGE(PG8_SB(1, 0), cB + kstep, voffB); PG8_STAGE(PG8_SA(1, 0), cA + kstep, voffA); PG8_STAGE(PG8_SB(1, 1), cB + hstep + kstep, voffB);
;         PG8_WAIT_V(6); PG8_BAR;
.LBB0_1312:
	s_lshl_b32 s10, s10, 5
	s_and_b32 s18, s10, 0x60
	s_lshl_b32 s15, s14, 13
	s_lshl_b32 s19, s18, 7
	s_add_u32 s10, s34, 0x1ed00000
	s_mov_b64 s[12:13], 0x80
	s_addc_u32 s11, s35, 0
	s_add_i32 m0, s25, 0x18000
	v_lshl_add_u64 v[8:9], v[8:9], 0, s[12:13]
	s_ashr_i32 s56, s96, 31
	global_load_lds_dwordx4 v[8:9], off
	v_lshl_add_u64 v[6:7], v[6:7], 0, s[12:13]
	s_add_i32 m0, s25, 0x1a000
	s_add_i32 s57, s25, 0x8000
	s_add_i32 s58, s25, 0xa000
	global_load_lds_dwordx4 v[6:7], off
	v_lshl_add_u64 v[2:3], v[2:3], 0, s[12:13]
	s_mov_b32 m0, s57
	s_add_u32 s16, s26, 0x10080
	global_load_lds_dwordx4 v[2:3], off
	v_lshl_add_u64 v[2:3], v[4:5], 0, s[12:13]
	s_mov_b32 m0, s58
	s_addc_u32 s17, s27, 0
	global_load_lds_dwordx4 v[2:3], off
	s_add_i32 m0, s25, 0x1c000
	v_lshl_add_u64 v[2:3], s[16:17], 0, v[134:135]
	global_load_lds_dwordx4 v[2:3], off
	v_lshl_add_u64 v[2:3], s[16:17], 0, v[130:131]
	s_add_i32 m0, s25, 0x1e000
	s_cmpk_lt_u32 s1, 0x100
	global_load_lds_dwordx4 v[2:3], off
	s_waitcnt vmcnt(8)
	s_barrier
	v_lshrrev_b32_e32 v3, 1, v10
	v_and_b32_e32 v3, 24, v3
	v_and_b32_e32 v2, 15, v10
	v_lshlrev_b32_e32 v4, 1, v3
	v_lshl_or_b32 v145, s14, 6, v2
	v_lshl_or_b32 v2, v2, 6, v4
	v_lshlrev_b32_e32 v4, 2, v10
	v_and_b32_e32 v4, 32, v4
	s_waitcnt vmcnt(6)
	v_bitop3_b32 v5, v2, s15, v4 bitop3:0xde
	v_bitop3_b32 v146, v2, s19, v4 bitop3:0xde
	s_cselect_b64 s[14:15], -1, 0
	s_add_i32 s59, 0, 0x10000
	s_add_i32 s60, 0, 0x14000
	s_sext_i32_i8 s61, s0
	v_or_b32_e32 v147, s18, v3
	v_mov_b64_e32 v[138:139], 0x110
	v_mov_b64_e32 v[140:141], 0x10f
	v_add_u32_e32 v148, s59, v146
	v_add_u32_e32 v149, s60, v146
	v_add_u32_e32 v150, 0, v5
	s_barrier
	s_branch .LBB0_1315

; #define PG8_STAGE(bufoff, gbase, voff) do { _Pragma("unroll") for (int _i = 0; _i < 2; ++_i) \
;         __builtin_amdgcn_global_load_lds((const unsigned*)((const char*)(gbase) + (voff)[_i]), (PG8_LAS unsigned*)(lds + (bufoff) + ldsw + _i * 8192), 16, 0, 0); } while (0)
; #define PG8_WAIT_V(n) asm volatile("s_waitcnt vmcnt(" #n ")" ::: "memory")
; #define PG8_BAR __builtin_amdgcn_s_barrier()
; template <class Epi, class Sched, bool ALIGN_EPI = false, bool SP2 = false>
; __device__ __forceinline__ void gemm_phase(PG8_LAS unsigned char* lds, const Gemm g, const Sched& S, const Epi& E) {
;     ...
;     const int tid = tid_, wid = __builtin_amdgcn_readfirstlane(tid >> 6), lane = tid & 63, wr = wid >> 2, wc = wid & 3, fr = lane & 15, fq = lane >> 4;
;     const int K = g.K, nt = __builtin_amdgcn_readfirstlane(g.nt);
;     unsigned voffA[2], voffB[2];
; #pragma unroll
;     for (int i = 0; i < 2; ++i) { int R, C; stage_rc(tid * 16 + i * 8192, R, C); const int Rb = Epi::PERM ? ((R & ~31) + perm32(R & 31)) : R;
;         voffA[i] = (unsigned)(R * K + C) * 2u; voffB[i] = (unsigned)(Rb * K + C) * 2u; }
;     const size_t kstep = (size_t)(BK * 2);
;     const size_t hstep = (size_t)HALF * K * 2;
;     const size_t tstep = 2 * hstep;
;     const unsigned ldsw = (unsigned)wid * 1024u;
;     const int aoff = lds_byte(wr * 64 + fr, fq * 8), boff = lds_byte(wc * 32 + fr, fq * 8);
;     ...
;     if constexpr (SP2) {
;         PG8_STAGE(PG8_SB(0, 0), cB, voffB); PG8_STAGE(PG8_SB(0, 1), cB + hstep, voffB); PG8_STAGE(PG8_SA(0, 0), cA, voffA); PG8_STAGE(PG8_SA(0, 1), cA + hstep, voffA);
;         if (wr == 1) PG8_BAR;
;         PG8_WAIT_V(2); PG8_BAR;
;         PG8_STAGE(PG8_SB(1, 0), cB + kstep, voffB); PG8_STAGE(PG8_SA(1, 0), cA + kstep, voffA); PG8_STAGE(PG8_SB(1, 1), cB + hstep + kstep, voffB);
;         PG8_WAIT_V(6); PG8_BAR;
.LBB0_1383:
	s_lshl_b32 s12, s12, 5
	s_and_b32 s18, s12, 0x60
	s_mov_b64 s[12:13], 0x80
	s_add_i32 m0, s25, 0x18000
	v_lshl_add_u64 v[8:9], v[8:9], 0, s[12:13]
	s_ashr_i32 s42, s96, 31
	s_lshl_b32 s15, s14, 13
	s_lshl_b32 s19, s18, 7
	global_load_lds_dwordx4 v[8:9], off
	v_lshl_add_u64 v[4:5], v[4:5], 0, s[12:13]
	s_add_i32 m0, s25, 0x1a000
	s_add_i32 s43, s25, 0x8000
	s_add_i32 s44, s25, 0xa000
	global_load_lds_dwordx4 v[4:5], off
	v_lshl_add_u64 v[2:3], v[2:3], 0, s[12:13]
	s_mov_b32 m0, s43
	s_add_u32 s16, s28, 0x80080
	global_load_lds_dwordx4 v[2:3], off
	v_lshl_add_u64 v[2:3], v[6:7], 0, s[12:13]
	s_mov_b32 m0, s44
	s_addc_u32 s17, s29, 0
	global_load_lds_dwordx4 v[2:3], off
	s_add_i32 m0, s25, 0x1c000
	v_lshl_add_u64 v[2:3], s[16:17], 0, v[134:135]
	global_load_lds_dwordx4 v[2:3], off
	v_lshl_add_u64 v[2:3], s[16:17], 0, v[130:131]
	s_add_i32 m0, s25, 0x1e000
	s_cmpk_lt_u32 s1, 0x100
	global_load_lds_dwordx4 v[2:3], off
	s_waitcnt vmcnt(8)
	s_barrier
	v_lshrrev_b32_e32 v3, 1, v11
	v_and_b32_e32 v3, 24, v3
	v_and_b32_e32 v2, 15, v11
	v_lshlrev_b32_e32 v4, 1, v3
	v_lshl_or_b32 v149, s14, 6, v2
	v_lshl_or_b32 v2, v2, 6, v4
	v_lshlrev_b32_e32 v4, 2, v11
	v_and_b32_e32 v4, 32, v4
	v_bitop3_b32 v5, v2, s15, v4 bitop3:0xde
	v_bitop3_b32 v150, v2, s19, v4 bitop3:0xde
	v_lshlrev_b32_e32 v2, 15, v15
	v_and_b32_e32 v2, 0xffff0000, v2
	v_or_b32_e32 v151, s18, v3
	v_lshl_add_u32 v2, v14, 12, v2
	v_and_b32_e32 v3, 1, v15
	v_lshl_or_b32 v2, v3, 6, v2
	v_lshl_add_u32 v138, v16, 1, v2
	v_lshlrev_b32_e32 v2, 15, v10
	v_and_b32_e32 v2, 0xffff0000, v2
	s_waitcnt vmcnt(6)
	v_lshl_add_u32 v2, v12, 12, v2
	v_and_b32_e32 v3, 1, v10
	s_cselect_b64 s[14:15], -1, 0
	v_lshl_or_b32 v2, v3, 6, v2
	s_add_i32 s45, 0, 0x10000
	s_add_i32 s46, 0, 0x14000
	s_sext_i32_i8 s47, s0
	v_mov_b32_e32 v139, v135
	v_lshl_add_u32 v140, v13, 1, v2
	v_mov_b32_e32 v141, v135
	v_mov_b64_e32 v[142:143], 0x100
	v_mov_b64_e32 v[144:145], 0xff
	v_add_u32_e32 v152, s45, v150
	v_add_u32_e32 v153, s46, v150
	v_add_u32_e32 v154, 0, v5
	s_barrier
	s_branch .LBB0_1386

; #define PG8_STAGE(bufoff, gbase, voff) do { _Pragma("unroll") for (int _i = 0; _i < 2; ++_i) \
;         __builtin_amdgcn_global_load_lds((const unsigned*)((const char*)(gbase) + (voff)[_i]), (PG8_LAS unsigned*)(lds + (bufoff) + ldsw + _i * 8192), 16, 0, 0); } while (0)
; #define PG8_WAIT_V(n) asm volatile("s_waitcnt vmcnt(" #n ")" ::: "memory")
; #define PG8_BAR __builtin_amdgcn_s_barrier()
; template <class Epi, class Sched, bool ALIGN_EPI = false, bool SP2 = false>
; __device__ __forceinline__ void gemm_phase(PG8_LAS unsigned char* lds, const Gemm g, const Sched& S, const Epi& E) {
;     ...
;     const int tid = tid_, wid = __builtin_amdgcn_readfirstlane(tid >> 6), lane = tid & 63, wr = wid >> 2, wc = wid & 3, fr = lane & 15, fq = lane >> 4;
;     const int K = g.K, nt = __builtin_amdgcn_readfirstlane(g.nt);
;     unsigned voffA[2], voffB[2];
; #pragma unroll
;     for (int i = 0; i < 2; ++i) { int R, C; stage_rc(tid * 16 + i * 8192, R, C); const int Rb = Epi::PERM ? ((R & ~31) + perm32(R & 31)) : R;
;         voffA[i] = (unsigned)(R * K + C) * 2u; voffB[i] = (unsigned)(Rb * K + C) * 2u; }
;     const size_t kstep = (size_t)(BK * 2);
;     const size_t hstep = (size_t)HALF * K * 2;
;     const size_t tstep = 2 * hstep;
;     const unsigned ldsw = (unsigned)wid * 1024u;
;     const int aoff = lds_byte(wr * 64 + fr, fq * 8), boff = lds_byte(wc * 32 + fr, fq * 8);
;     ...
;     if constexpr (SP2) {
;         PG8_STAGE(PG8_SB(0, 0), cB, voffB); PG8_STAGE(PG8_SB(0, 1), cB + hstep, voffB); PG8_STAGE(PG8_SA(0, 0), cA, voffA); PG8_STAGE(PG8_SA(0, 1), cA + hstep, voffA);
;         if (wr == 1) PG8_BAR;
;         PG8_WAIT_V(2); PG8_BAR;
;         PG8_STAGE(PG8_SB(1, 0), cB + kstep, voffB); PG8_STAGE(PG8_SA(1, 0), cA + kstep, voffA); PG8_STAGE(PG8_SB(1, 1), cB + hstep + kstep, voffB);
;         PG8_WAIT_V(6); PG8_BAR;
.LBB0_1418:
	s_lshl_b32 s12, s12, 5
	s_and_b32 s20, s12, 0x60
	s_lshl_b32 s7, s1, 13
	s_lshl_b32 s21, s20, 7
	s_add_u32 s55, s34, 0x3ab00000
	s_addc_u32 s56, s35, 0
	s_add_u32 s18, s14, 0x80080
	s_mov_b64 s[12:13], 0x80
	s_addc_u32 s19, s15, 0
	s_add_i32 m0, s51, 0x18000
	v_lshl_add_u64 v[8:9], v[8:9], 0, s[12:13]
	global_load_lds_dwordx4 v[8:9], off
	v_lshl_add_u64 v[6:7], v[6:7], 0, s[12:13]
	s_add_i32 m0, s51, 0x1a000
	s_add_i32 s57, s51, 0x8000
	global_load_lds_dwordx4 v[6:7], off
	v_lshl_add_u64 v[2:3], v[2:3], 0, s[12:13]
	s_mov_b32 m0, s57
	s_add_i32 s58, s51, 0xa000
	global_load_lds_dwordx4 v[2:3], off
	v_lshl_add_u64 v[2:3], v[4:5], 0, s[12:13]
	s_mov_b32 m0, s58
	s_mov_b32 s59, 0
	global_load_lds_dwordx4 v[2:3], off
	s_add_i32 m0, s51, 0x1c000
	v_lshl_add_u64 v[2:3], s[18:19], 0, v[132:133]
	global_load_lds_dwordx4 v[2:3], off
	v_lshl_add_u64 v[2:3], s[18:19], 0, v[130:131]
	s_add_i32 m0, s51, 0x1e000
	s_cmpk_lt_u32 s0, 0x100
	global_load_lds_dwordx4 v[2:3], off
	s_waitcnt vmcnt(8)
	s_barrier
	v_bfe_u32 v2, v10, 4, 2
	v_and_b32_e32 v3, 15, v10
	v_lshlrev_b32_e32 v5, 4, v2
	v_lshl_or_b32 v4, s1, 6, v3
	v_lshl_or_b32 v3, v3, 6, v5
	v_lshlrev_b32_e32 v5, 2, v10
	v_and_b32_e32 v5, 32, v5
	s_waitcnt vmcnt(6)
	v_bitop3_b32 v6, v3, s7, v5 bitop3:0xde
	v_bitop3_b32 v134, v3, s21, v5 bitop3:0xde
	s_cselect_b64 s[18:19], -1, 0
	s_add_i32 s60, 0, 0x10000
	s_add_i32 s61, 0, 0x14000
	v_add_u32_e32 v135, 0xffffe000, v4
	v_lshl_or_b32 v136, v2, 2, s20
	v_add_u32_e32 v137, s60, v134
	v_add_u32_e32 v138, s61, v134
	v_add_u32_e32 v139, 0, v6
	s_mov_b32 s62, s45
	s_mov_b32 s63, s50
	s_barrier
	s_branch .LBB0_1421

; #define PG8_STAGE(bufoff, gbase, voff) do { _Pragma("unroll") for (int _i = 0; _i < 2; ++_i) \
;         __builtin_amdgcn_global_load_lds((const unsigned*)((const char*)(gbase) + (voff)[_i]), (PG8_LAS unsigned*)(lds + (bufoff) + ldsw + _i * 8192), 16, 0, 0); } while (0)
; #define PG8_WAIT_V(n) asm volatile("s_waitcnt vmcnt(" #n ")" ::: "memory")
; #define PG8_BAR __builtin_amdgcn_s_barrier()
; template <class Epi, class Sched, bool ALIGN_EPI = false, bool SP2 = false>
; __device__ __forceinline__ void gemm_phase(PG8_LAS unsigned char* lds, const Gemm g, const Sched& S, const Epi& E) {
;     ...
;     const int tid = tid_, wid = __builtin_amdgcn_readfirstlane(tid >> 6), lane = tid & 63, wr = wid >> 2, wc = wid & 3, fr = lane & 15, fq = lane >> 4;
;     const int K = g.K, nt = __builtin_amdgcn_readfirstlane(g.nt);
;     unsigned voffA[2], voffB[2];
; #pragma unroll
;     for (int i = 0; i < 2; ++i) { int R, C; stage_rc(tid * 16 + i * 8192, R, C); const int Rb = Epi::PERM ? ((R & ~31) + perm32(R & 31)) : R;
;         voffA[i] = (unsigned)(R * K + C) * 2u; voffB[i] = (unsigned)(Rb * K + C) * 2u; }
;     const size_t kstep = (size_t)(BK * 2);
;     const size_t hstep = (size_t)HALF * K * 2;
;     const size_t tstep = 2 * hstep;
;     const unsigned ldsw = (unsigned)wid * 1024u;
;     const int aoff = lds_byte(wr * 64 + fr, fq * 8), boff = lds_byte(wc * 32 + fr, fq * 8);
;     ...
;     if constexpr (SP2) {
;         PG8_STAGE(PG8_SB(0, 0), cB, voffB); PG8_STAGE(PG8_SB(0, 1), cB + hstep, voffB); PG8_STAGE(PG8_SA(0, 0), cA, voffA); PG8_STAGE(PG8_SA(0, 1), cA + hstep, voffA);
;         if (wr == 1) PG8_BAR;
;         PG8_WAIT_V(2); PG8_BAR;
;         PG8_STAGE(PG8_SB(1, 0), cB + kstep, voffB); PG8_STAGE(PG8_SA(1, 0), cA + kstep, voffA); PG8_STAGE(PG8_SB(1, 1), cB + hstep + kstep, voffB);
;         PG8_WAIT_V(6); PG8_BAR;
.LBB0_1545:
	s_lshl_b32 s10, s10, 5
	s_and_b32 s16, s10, 0x60
	s_mov_b64 s[10:11], 0x80
	s_add_i32 m0, s23, 0x18000
	v_lshl_add_u64 v[8:9], v[8:9], 0, s[10:11]
	s_ashr_i32 s41, s96, 31
	s_lshl_b32 s13, s12, 13
	s_lshl_b32 s17, s16, 7
	global_load_lds_dwordx4 v[8:9], off
	v_lshl_add_u64 v[6:7], v[6:7], 0, s[10:11]
	s_add_i32 m0, s23, 0x1a000
	s_add_i32 s42, s23, 0x8000
	s_add_i32 s43, s23, 0xa000
	global_load_lds_dwordx4 v[6:7], off
	v_lshl_add_u64 v[2:3], v[2:3], 0, s[10:11]
	s_mov_b32 m0, s42
	s_add_u32 s14, s26, 0x80080
	global_load_lds_dwordx4 v[2:3], off
	v_lshl_add_u64 v[2:3], v[4:5], 0, s[10:11]
	s_mov_b32 m0, s43
	s_addc_u32 s15, s27, 0
	global_load_lds_dwordx4 v[2:3], off
	s_add_i32 m0, s23, 0x1c000
	v_lshl_add_u64 v[2:3], s[14:15], 0, v[134:135]
	global_load_lds_dwordx4 v[2:3], off
	v_lshl_add_u64 v[2:3], s[14:15], 0, v[130:131]
	s_add_i32 m0, s23, 0x1e000
	s_cmpk_lt_u32 s1, 0x100
	global_load_lds_dwordx4 v[2:3], off
	s_waitcnt vmcnt(8)
	s_barrier
	v_lshrrev_b32_e32 v3, 1, v11
	v_and_b32_e32 v3, 24, v3
	v_and_b32_e32 v2, 15, v11
	v_lshlrev_b32_e32 v4, 1, v3
	v_lshl_or_b32 v150, s12, 6, v2
	v_lshl_or_b32 v2, v2, 6, v4
	v_lshlrev_b32_e32 v4, 2, v11
	v_and_b32_e32 v4, 32, v4
	v_bitop3_b32 v5, v2, s13, v4 bitop3:0xde
	v_bitop3_b32 v151, v2, s17, v4 bitop3:0xde
	v_lshlrev_b32_e32 v2, 15, v15
	v_and_b32_e32 v2, 0xffff0000, v2
	v_or_b32_e32 v152, s16, v3
	v_lshl_add_u32 v2, v14, 12, v2
	v_and_b32_e32 v3, 1, v15
	v_lshl_or_b32 v2, v3, 6, v2
	v_lshl_add_u32 v138, v16, 1, v2
	v_lshlrev_b32_e32 v2, 15, v10
	v_and_b32_e32 v2, 0xffff0000, v2
	s_waitcnt vmcnt(6)
	v_lshl_add_u32 v2, v12, 12, v2
	v_and_b32_e32 v3, 1, v10
	s_cselect_b64 s[12:13], -1, 0
	v_lshl_or_b32 v2, v3, 6, v2
	s_add_i32 s44, 0, 0x10000
	s_add_i32 s45, 0, 0x14000
	s_sext_i32_i16 s47, s0
	v_mov_b32_e32 v139, v135
	v_lshl_add_u32 v140, v13, 1, v2
	v_mov_b32_e32 v141, v135
	v_mov_b64_e32 v[142:143], 0x5d8
	v_mov_b64_e32 v[144:145], 0x5d7
	v_add_u32_e32 v153, s44, v151
	v_add_u32_e32 v154, s45, v151
	v_add_u32_e32 v155, 0, v5
	s_movk_i32 s46, 0x2c00
	s_barrier
	s_branch .LBB0_1548

; #define PG8_STAGE(bufoff, gbase, voff) do { _Pragma("unroll") for (int _i = 0; _i < 2; ++_i) \
;         __builtin_amdgcn_global_load_lds((const unsigned*)((const char*)(gbase) + (voff)[_i]), (PG8_LAS unsigned*)(lds + (bufoff) + ldsw + _i * 8192), 16, 0, 0); } while (0)
; #define PG8_WAIT_V(n) asm volatile("s_waitcnt vmcnt(" #n ")" ::: "memory")
; #define PG8_BAR __builtin_amdgcn_s_barrier()
; template <class Epi, class Sched, bool ALIGN_EPI = false, bool SP2 = false>
; __device__ __forceinline__ void gemm_phase(PG8_LAS unsigned char* lds, const Gemm g, const Sched& S, const Epi& E) {
;     ...
;     const int tid = tid_, wid = __builtin_amdgcn_readfirstlane(tid >> 6), lane = tid & 63, wr = wid >> 2, wc = wid & 3, fr = lane & 15, fq = lane >> 4;
;     const int K = g.K, nt = __builtin_amdgcn_readfirstlane(g.nt);
;     unsigned voffA[2], voffB[2];
; #pragma unroll
;     for (int i = 0; i < 2; ++i) { int R, C; stage_rc(tid * 16 + i * 8192, R, C); const int Rb = Epi::PERM ? ((R & ~31) + perm32(R & 31)) : R;
;         voffA[i] = (unsigned)(R * K + C) * 2u; voffB[i] = (unsigned)(Rb * K + C) * 2u; }
;     const size_t kstep = (size_t)(BK * 2);
;     const size_t hstep = (size_t)HALF * K * 2;
;     const size_t tstep = 2 * hstep;
;     const unsigned ldsw = (unsigned)wid * 1024u;
;     const int aoff = lds_byte(wr * 64 + fr, fq * 8), boff = lds_byte(wc * 32 + fr, fq * 8);
;     ...
;     if constexpr (SP2) {
;         PG8_STAGE(PG8_SB(0, 0), cB, voffB); PG8_STAGE(PG8_SB(0, 1), cB + hstep, voffB); PG8_STAGE(PG8_SA(0, 0), cA, voffA); PG8_STAGE(PG8_SA(0, 1), cA + hstep, voffA);
;         if (wr == 1) PG8_BAR;
;         PG8_WAIT_V(2); PG8_BAR;
;         PG8_STAGE(PG8_SB(1, 0), cB + kstep, voffB); PG8_STAGE(PG8_SA(1, 0), cA + kstep, voffA); PG8_STAGE(PG8_SB(1, 1), cB + hstep + kstep, voffB);
;         PG8_WAIT_V(6); PG8_BAR;
.LBB0_1642:
	s_lshl_b32 s7, s7, 5
	s_mov_b64 s[10:11], 0x80
	s_and_b32 s7, s7, 0x60
	s_add_i32 m0, s38, 0x18000
	v_lshl_add_u64 v[8:9], v[8:9], 0, s[10:11]
	s_ashr_i32 s43, s96, 31
	s_lshl_b32 s13, s1, 13
	s_lshl_b32 s15, s7, 7
	global_load_lds_dwordx4 v[8:9], off
	v_lshl_add_u64 v[4:5], v[4:5], 0, s[10:11]
	s_add_i32 m0, s38, 0x1a000
	s_add_i32 s44, s38, 0x8000
	s_add_i32 s45, s38, 0xa000
	global_load_lds_dwordx4 v[4:5], off
	v_lshl_add_u64 v[2:3], v[2:3], 0, s[10:11]
	s_mov_b32 m0, s44
	s_add_u32 s16, s26, 0x160080
	global_load_lds_dwordx4 v[2:3], off
	v_lshl_add_u64 v[2:3], v[6:7], 0, s[10:11]
	s_mov_b32 m0, s45
	s_addc_u32 s17, s27, 0
	global_load_lds_dwordx4 v[2:3], off
	s_add_i32 m0, s38, 0x1c000
	v_lshl_add_u64 v[2:3], s[16:17], 0, v[134:135]
	global_load_lds_dwordx4 v[2:3], off
	v_lshl_add_u64 v[2:3], s[16:17], 0, v[130:131]
	s_add_i32 m0, s38, 0x1e000
	s_cmpk_lt_u32 s0, 0x100
	global_load_lds_dwordx4 v[2:3], off
	s_waitcnt vmcnt(8)
	s_barrier
	v_lshrrev_b32_e32 v3, 1, v11
	v_and_b32_e32 v3, 24, v3
	v_and_b32_e32 v2, 15, v11
	v_lshlrev_b32_e32 v4, 1, v3
	v_lshl_or_b32 v148, s1, 6, v2
	v_lshl_or_b32 v2, v2, 6, v4
	v_lshlrev_b32_e32 v4, 2, v11
	v_and_b32_e32 v4, 32, v4
	v_bitop3_b32 v5, v2, s13, v4 bitop3:0xde
	v_bitop3_b32 v149, v2, s15, v4 bitop3:0xde
	v_or_b32_e32 v150, s7, v3
	v_lshrrev_b32_e32 v3, 1, v16
	v_mul_lo_u32 v2, v15, s6
	v_mad_u64_u32 v[2:3], s[0:1], v3, s14, v[2:3]
	v_or_b32_e32 v2, v2, v17
	s_mov_b64 s[16:17], 0x160080
	v_add_lshl_u32 v2, v2, v18, 1
	v_mov_b32_e32 v3, v135
	v_lshl_add_u64 v[138:139], v[2:3], 0, s[16:17]
	v_lshrrev_b32_e32 v3, 1, v10
	v_mul_lo_u32 v2, v12, s6
	v_mad_u64_u32 v[2:3], s[0:1], v3, s14, v[2:3]
	s_waitcnt vmcnt(6)
	v_or_b32_e32 v2, v2, v13
	s_sext_i32_i8 s55, s12
	s_cselect_b64 s[12:13], -1, 0
	v_add_lshl_u32 v2, v2, v14, 1
	v_mov_b32_e32 v3, v135
	s_add_i32 s46, 0, 0x10000
	s_add_i32 s47, 0, 0x14000
	v_lshl_add_u64 v[140:141], v[2:3], 0, s[16:17]
	v_mov_b64_e32 v[142:143], 0x100
	v_mov_b64_e32 v[144:145], 0xff
	v_add_u32_e32 v151, s46, v149
	v_add_u32_e32 v152, s47, v149
	v_add_u32_e32 v153, 0, v5
	s_mov_b64 s[14:15], 0x80000
	s_mov_b32 s48, 0x80000
	s_mov_b64 s[16:17], 0x90000
	s_mov_b32 s49, 0x90000
	s_mov_b64 s[18:19], 0xa0000
	s_mov_b32 s50, 0xa0000
	s_mov_b64 s[20:21], 0xb0000
	s_mov_b32 s51, 0xb0000
	s_barrier
	s_branch .LBB0_1645

; #define PG8_STAGE(bufoff, gbase, voff) do { _Pragma("unroll") for (int _i = 0; _i < 2; ++_i) \
;         __builtin_amdgcn_global_load_lds((const unsigned*)((const char*)(gbase) + (voff)[_i]), (PG8_LAS unsigned*)(lds + (bufoff) + ldsw + _i * 8192), 16, 0, 0); } while (0)
; #define PG8_WAIT_V(n) asm volatile("s_waitcnt vmcnt(" #n ")" ::: "memory")
; #define PG8_BAR __builtin_amdgcn_s_barrier()
; template <class Epi, class Sched, bool ALIGN_EPI = false, bool SP2 = false>
; __device__ __forceinline__ void gemm_phase(PG8_LAS unsigned char* lds, const Gemm g, const Sched& S, const Epi& E) {
;     ...
;     const int tid = tid_, wid = __builtin_amdgcn_readfirstlane(tid >> 6), lane = tid & 63, wr = wid >> 2, wc = wid & 3, fr = lane & 15, fq = lane >> 4;
;     const int K = g.K, nt = __builtin_amdgcn_readfirstlane(g.nt);
;     unsigned voffA[2], voffB[2];
; #pragma unroll
;     for (int i = 0; i < 2; ++i) { int R, C; stage_rc(tid * 16 + i * 8192, R, C); const int Rb = Epi::PERM ? ((R & ~31) + perm32(R & 31)) : R;
;         voffA[i] = (unsigned)(R * K + C) * 2u; voffB[i] = (unsigned)(Rb * K + C) * 2u; }
;     const size_t kstep = (size_t)(BK * 2);
;     const size_t hstep = (size_t)HALF * K * 2;
;     const size_t tstep = 2 * hstep;
;     const unsigned ldsw = (unsigned)wid * 1024u;
;     const int aoff = lds_byte(wr * 64 + fr, fq * 8), boff = lds_byte(wc * 32 + fr, fq * 8);
;     ...
;     if constexpr (SP2) {
;         PG8_STAGE(PG8_SB(0, 0), cB, voffB); PG8_STAGE(PG8_SB(0, 1), cB + hstep, voffB); PG8_STAGE(PG8_SA(0, 0), cA, voffA); PG8_STAGE(PG8_SA(0, 1), cA + hstep, voffA);
;         if (wr == 1) PG8_BAR;
;         PG8_WAIT_V(2); PG8_BAR;
;         PG8_STAGE(PG8_SB(1, 0), cB + kstep, voffB); PG8_STAGE(PG8_SA(1, 0), cA + kstep, voffA); PG8_STAGE(PG8_SB(1, 1), cB + hstep + kstep, voffB);
;         PG8_WAIT_V(6); PG8_BAR;
.LBB0_1666:
	s_lshl_b32 s12, s12, 5
	s_and_b32 s20, s12, 0x60
	s_lshl_b32 s17, s1, 13
	s_lshl_b32 s18, s20, 7
	s_add_u32 s45, s34, 0x3ab00000
	s_addc_u32 s46, s35, 0
	s_add_u32 s14, s28, 0x160080
	s_mov_b64 s[12:13], 0x80
	s_addc_u32 s15, s29, 0
	s_add_i32 m0, s41, 0x18000
	v_lshl_add_u64 v[8:9], v[8:9], 0, s[12:13]
	global_load_lds_dwordx4 v[8:9], off
	v_lshl_add_u64 v[6:7], v[6:7], 0, s[12:13]
	s_add_i32 m0, s41, 0x1a000
	s_add_i32 s47, s41, 0x8000
	global_load_lds_dwordx4 v[6:7], off
	v_lshl_add_u64 v[2:3], v[2:3], 0, s[12:13]
	s_mov_b32 m0, s47
	s_add_i32 s48, s41, 0xa000
	global_load_lds_dwordx4 v[2:3], off
	v_lshl_add_u64 v[2:3], v[4:5], 0, s[12:13]
	s_mov_b32 m0, s48
	s_mov_b32 s49, 0
	global_load_lds_dwordx4 v[2:3], off
	s_add_i32 m0, s41, 0x1c000
	v_lshl_add_u64 v[2:3], s[14:15], 0, v[132:133]
	global_load_lds_dwordx4 v[2:3], off
	v_lshl_add_u64 v[2:3], s[14:15], 0, v[130:131]
	s_add_i32 m0, s41, 0x1e000
	s_cmpk_lt_u32 s0, 0x100
	global_load_lds_dwordx4 v[2:3], off
	s_waitcnt vmcnt(8)
	s_barrier
	v_bfe_u32 v2, v10, 4, 2
	v_and_b32_e32 v3, 15, v10
	v_lshlrev_b32_e32 v5, 4, v2
	v_lshl_or_b32 v4, s1, 6, v3
	v_lshl_or_b32 v3, v3, 6, v5
	v_lshlrev_b32_e32 v5, 2, v10
	v_and_b32_e32 v5, 32, v5
	v_bitop3_b32 v6, v3, s17, v5 bitop3:0xde
	v_bitop3_b32 v138, v3, s18, v5 bitop3:0xde
	v_lshl_or_b32 v140, v2, 2, s20
	v_lshrrev_b32_e32 v3, 1, v16
	v_mul_lo_u32 v2, v15, s7
	v_mad_u64_u32 v[2:3], s[0:1], v3, s16, v[2:3]
	v_or_b32_e32 v2, v2, v17
	s_mov_b64 s[18:19], 0x160080
	v_add_lshl_u32 v2, v2, v18, 1
	v_mov_b32_e32 v3, v133
	v_lshl_add_u64 v[134:135], v[2:3], 0, s[18:19]
	v_lshrrev_b32_e32 v3, 1, v11
	v_mul_lo_u32 v2, v12, s7
	v_mad_u64_u32 v[2:3], s[0:1], v3, s16, v[2:3]
	s_waitcnt vmcnt(6)
	v_or_b32_e32 v2, v2, v13
	s_cselect_b64 s[14:15], -1, 0
	v_add_lshl_u32 v2, v2, v14, 1
	v_mov_b32_e32 v3, v133
	s_add_i32 s50, 0, 0x10000
	s_add_i32 s51, 0, 0x14000
	v_add_u32_e32 v139, 0xffffe000, v4
	v_lshl_add_u64 v[136:137], v[2:3], 0, s[18:19]
	v_add_u32_e32 v141, s50, v138
	v_add_u32_e32 v142, s51, v138
	v_add_u32_e32 v143, 0, v6
	s_mov_b64 s[16:17], 0x100000
	s_mov_b32 s52, 0x100000
	s_mov_b64 s[18:19], 0x120000
	s_mov_b32 s53, 0x120000
	s_mov_b64 s[20:21], 0x140000
	s_mov_b32 s54, 0x140000
	s_mov_b32 s57, s38
	s_mov_b32 s58, s40
	s_barrier
	s_branch .LBB0_1669

; #define PG8_STAGE(bufoff, gbase, voff) do { _Pragma("unroll") for (int _i = 0; _i < 2; ++_i) \
;         __builtin_amdgcn_global_load_lds((const unsigned*)((const char*)(gbase) + (voff)[_i]), (PG8_LAS unsigned*)(lds + (bufoff) + ldsw + _i * 8192), 16, 0, 0); } while (0)
; #define PG8_WAIT_V(n) asm volatile("s_waitcnt vmcnt(" #n ")" ::: "memory")
; #define PG8_BAR __builtin_amdgcn_s_barrier()
; template <class Epi, class Sched, bool ALIGN_EPI = false, bool SP2 = false>
; __device__ __forceinline__ void gemm_phase(PG8_LAS unsigned char* lds, const Gemm g, const Sched& S, const Epi& E) {
;     ...
;     const int tid = tid_, wid = __builtin_amdgcn_readfirstlane(tid >> 6), lane = tid & 63, wr = wid >> 2, wc = wid & 3, fr = lane & 15, fq = lane >> 4;
;     const int K = g.K, nt = __builtin_amdgcn_readfirstlane(g.nt);
;     unsigned voffA[2], voffB[2];
; #pragma unroll
;     for (int i = 0; i < 2; ++i) { int R, C; stage_rc(tid * 16 + i * 8192, R, C); const int Rb = Epi::PERM ? ((R & ~31) + perm32(R & 31)) : R;
;         voffA[i] = (unsigned)(R * K + C) * 2u; voffB[i] = (unsigned)(Rb * K + C) * 2u; }
;     const size_t kstep = (size_t)(BK * 2);
;     const size_t hstep = (size_t)HALF * K * 2;
;     const size_t tstep = 2 * hstep;
;     const unsigned ldsw = (unsigned)wid * 1024u;
;     const int aoff = lds_byte(wr * 64 + fr, fq * 8), boff = lds_byte(wc * 32 + fr, fq * 8);
;     ...
;     if constexpr (SP2) {
;         PG8_STAGE(PG8_SB(0, 0), cB, voffB); PG8_STAGE(PG8_SB(0, 1), cB + hstep, voffB); PG8_STAGE(PG8_SA(0, 0), cA, voffA); PG8_STAGE(PG8_SA(0, 1), cA + hstep, voffA);
;         if (wr == 1) PG8_BAR;
;         PG8_WAIT_V(2); PG8_BAR;
;         PG8_STAGE(PG8_SB(1, 0), cB + kstep, voffB); PG8_STAGE(PG8_SA(1, 0), cA + kstep, voffA); PG8_STAGE(PG8_SB(1, 1), cB + hstep + kstep, voffB);
;         PG8_WAIT_V(6); PG8_BAR;
.LBB0_1687:
	s_lshl_b32 s8, s8, 5
	s_and_b32 s15, s8, 0x60
	s_lshl_b32 s14, s1, 13
	s_lshl_b32 s16, s15, 7
	s_add_u32 s8, s34, 0x1ed00000
	s_mov_b64 s[10:11], 0x80
	s_addc_u32 s9, s35, 0
	s_add_i32 m0, s50, 0x18000
	v_lshl_add_u64 v[8:9], v[8:9], 0, s[10:11]
	global_load_lds_dwordx4 v[8:9], off
	v_lshl_add_u64 v[6:7], v[6:7], 0, s[10:11]
	s_add_i32 m0, s50, 0x1a000
	s_add_i32 s55, s50, 0x8000
	s_add_i32 s56, s50, 0xa000
	global_load_lds_dwordx4 v[6:7], off
	v_lshl_add_u64 v[2:3], v[2:3], 0, s[10:11]
	s_mov_b32 m0, s55
	s_add_u32 s12, s24, 0x10080
	global_load_lds_dwordx4 v[2:3], off
	v_lshl_add_u64 v[2:3], v[4:5], 0, s[10:11]
	s_mov_b32 m0, s56
	s_addc_u32 s13, s25, 0
	global_load_lds_dwordx4 v[2:3], off
	s_add_i32 m0, s50, 0x1c000
	v_lshl_add_u64 v[2:3], s[12:13], 0, v[134:135]
	global_load_lds_dwordx4 v[2:3], off
	v_lshl_add_u64 v[2:3], s[12:13], 0, v[130:131]
	s_add_i32 m0, s50, 0x1e000
	s_cmpk_lt_u32 s0, 0x100
	global_load_lds_dwordx4 v[2:3], off
	s_waitcnt vmcnt(8)
	s_barrier
	v_lshrrev_b32_e32 v3, 1, v10
	v_and_b32_e32 v3, 24, v3
	v_and_b32_e32 v2, 15, v10
	v_lshlrev_b32_e32 v4, 1, v3
	v_lshl_or_b32 v144, s1, 6, v2
	v_lshl_or_b32 v2, v2, 6, v4
	v_lshlrev_b32_e32 v4, 2, v10
	v_and_b32_e32 v4, 32, v4
	s_waitcnt vmcnt(6)
	v_bitop3_b32 v5, v2, s14, v4 bitop3:0xde
	v_bitop3_b32 v145, v2, s16, v4 bitop3:0xde
	s_cselect_b64 s[12:13], -1, 0
	s_add_i32 s57, 0, 0x10000
	s_add_i32 s58, 0, 0x14000
	v_or_b32_e32 v146, s15, v3
	v_mov_b64_e32 v[138:139], 0x110
	v_mov_b64_e32 v[140:141], 0x10f
	v_add_u32_e32 v147, s57, v145
	v_add_u32_e32 v148, s58, v145
	v_add_u32_e32 v149, 0, v5
	s_mov_b32 s59, 0xa0000
	s_mov_b64 s[14:15], 0xb0000
	s_mov_b32 s60, 0xb0000
	s_barrier
	s_branch .LBB0_1690

; #define PG8_STAGE(bufoff, gbase, voff) do { _Pragma("unroll") for (int _i = 0; _i < 2; ++_i) \
;         __builtin_amdgcn_global_load_lds((const unsigned*)((const char*)(gbase) + (voff)[_i]), (PG8_LAS unsigned*)(lds + (bufoff) + ldsw + _i * 8192), 16, 0, 0); } while (0)
; #define PG8_WAIT_V(n) asm volatile("s_waitcnt vmcnt(" #n ")" ::: "memory")
; #define PG8_BAR __builtin_amdgcn_s_barrier()
; template <class Epi, class Sched, bool ALIGN_EPI = false, bool SP2 = false>
; __device__ __forceinline__ void gemm_phase(PG8_LAS unsigned char* lds, const Gemm g, const Sched& S, const Epi& E) {
;     ...
;     const int tid = tid_, wid = __builtin_amdgcn_readfirstlane(tid >> 6), lane = tid & 63, wr = wid >> 2, wc = wid & 3, fr = lane & 15, fq = lane >> 4;
;     const int K = g.K, nt = __builtin_amdgcn_readfirstlane(g.nt);
;     unsigned voffA[2], voffB[2];
; #pragma unroll
;     for (int i = 0; i < 2; ++i) { int R, C; stage_rc(tid * 16 + i * 8192, R, C); const int Rb = Epi::PERM ? ((R & ~31) + perm32(R & 31)) : R;
;         voffA[i] = (unsigned)(R * K + C) * 2u; voffB[i] = (unsigned)(Rb * K + C) * 2u; }
;     const size_t kstep = (size_t)(BK * 2);
;     const size_t hstep = (size_t)HALF * K * 2;
;     const size_t tstep = 2 * hstep;
;     const unsigned ldsw = (unsigned)wid * 1024u;
;     const int aoff = lds_byte(wr * 64 + fr, fq * 8), boff = lds_byte(wc * 32 + fr, fq * 8);
;     ...
;     if constexpr (SP2) {
;         PG8_STAGE(PG8_SB(0, 0), cB, voffB); PG8_STAGE(PG8_SB(0, 1), cB + hstep, voffB); PG8_STAGE(PG8_SA(0, 0), cA, voffA); PG8_STAGE(PG8_SA(0, 1), cA + hstep, voffA);
;         if (wr == 1) PG8_BAR;
;         PG8_WAIT_V(2); PG8_BAR;
;         PG8_STAGE(PG8_SB(1, 0), cB + kstep, voffB); PG8_STAGE(PG8_SA(1, 0), cA + kstep, voffA); PG8_STAGE(PG8_SB(1, 1), cB + hstep + kstep, voffB);
;         PG8_WAIT_V(6); PG8_BAR;
.LBB0_1810:
	s_add_u32 s10, s34, 0x1ed00000
	s_addc_u32 s11, s35, 0
	s_lshl_b32 s12, s12, 5
	s_and_b32 s18, s12, 0x60
	s_mov_b64 s[12:13], 0x80
	s_add_i32 m0, s31, 0x18000
	v_lshl_add_u64 v[8:9], v[8:9], 0, s[12:13]
	s_ashr_i32 s47, s96, 31
	s_lshl_b32 s15, s14, 13
	s_lshl_b32 s19, s18, 7
	global_load_lds_dwordx4 v[8:9], off
	v_lshl_add_u64 v[4:5], v[4:5], 0, s[12:13]
	s_add_i32 m0, s31, 0x1a000
	s_add_i32 s48, s31, 0x8000
	s_add_i32 s49, s31, 0xa000
	global_load_lds_dwordx4 v[4:5], off
	v_lshl_add_u64 v[2:3], v[2:3], 0, s[12:13]
	s_mov_b32 m0, s48
	s_add_u32 s16, s38, 0x80080
	global_load_lds_dwordx4 v[2:3], off
	v_lshl_add_u64 v[2:3], v[6:7], 0, s[12:13]
	s_mov_b32 m0, s49
	s_addc_u32 s17, s39, 0
	global_load_lds_dwordx4 v[2:3], off
	s_add_i32 m0, s31, 0x1c000
	v_lshl_add_u64 v[2:3], s[16:17], 0, v[134:135]
	global_load_lds_dwordx4 v[2:3], off
	v_lshl_add_u64 v[2:3], s[16:17], 0, v[130:131]
	s_add_i32 m0, s31, 0x1e000
	s_cmpk_lt_u32 s1, 0x100
	global_load_lds_dwordx4 v[2:3], off
	s_waitcnt vmcnt(8)
	s_barrier
	v_lshrrev_b32_e32 v3, 1, v11
	v_and_b32_e32 v3, 24, v3
	v_and_b32_e32 v2, 15, v11
	v_lshlrev_b32_e32 v4, 1, v3
	v_lshl_or_b32 v152, s14, 6, v2
	v_lshl_or_b32 v2, v2, 6, v4
	v_lshlrev_b32_e32 v4, 2, v11
	v_and_b32_e32 v4, 32, v4
	v_bitop3_b32 v5, v2, s15, v4 bitop3:0xde
	v_bitop3_b32 v153, v2, s19, v4 bitop3:0xde
	v_lshlrev_b32_e32 v2, 15, v15
	v_and_b32_e32 v2, 0xffff0000, v2
	v_or_b32_e32 v154, s18, v3
	v_lshl_add_u32 v2, v14, 12, v2
	v_and_b32_e32 v3, 1, v15
	v_lshl_or_b32 v2, v3, 6, v2
	v_lshl_add_u32 v138, v16, 1, v2
	v_lshlrev_b32_e32 v2, 15, v10
	v_and_b32_e32 v2, 0xffff0000, v2
	s_waitcnt vmcnt(6)
	v_lshl_add_u32 v2, v12, 12, v2
	v_and_b32_e32 v3, 1, v10
	s_cselect_b64 s[14:15], -1, 0
	v_lshl_or_b32 v2, v3, 6, v2
	s_add_i32 s51, 0, 0x10000
	s_add_i32 s52, 0, 0x14000
	s_sext_i32_i8 s53, s0
	v_mov_b32_e32 v139, v135
	v_lshl_add_u32 v140, v13, 1, v2
	v_mov_b32_e32 v141, v135
	v_mov_b64_e32 v[142:143], 0x100
	v_mov_b64_e32 v[144:145], 0xff
	v_add_u32_e32 v155, s51, v153
	v_add_u32_e32 v156, s52, v153
	v_add_u32_e32 v157, 0, v5
	s_mov_b64 s[16:17], 0x90000
	s_mov_b64 s[18:19], 0xa0000
	s_mov_b64 s[20:21], 0xb0000
	s_barrier
	s_branch .LBB0_1813

; #define PG8_STAGE(bufoff, gbase, voff) do { _Pragma("unroll") for (int _i = 0; _i < 2; ++_i) \
;         __builtin_amdgcn_global_load_lds((const unsigned*)((const char*)(gbase) + (voff)[_i]), (PG8_LAS unsigned*)(lds + (bufoff) + ldsw + _i * 8192), 16, 0, 0); } while (0)
; #define PG8_WAIT_V(n) asm volatile("s_waitcnt vmcnt(" #n ")" ::: "memory")
; #define PG8_BAR __builtin_amdgcn_s_barrier()
; template <class Epi, class Sched, bool ALIGN_EPI = false, bool SP2 = false>
; __device__ __forceinline__ void gemm_phase(PG8_LAS unsigned char* lds, const Gemm g, const Sched& S, const Epi& E) {
;     ...
;     const int tid = tid_, wid = __builtin_amdgcn_readfirstlane(tid >> 6), lane = tid & 63, wr = wid >> 2, wc = wid & 3, fr = lane & 15, fq = lane >> 4;
;     const int K = g.K, nt = __builtin_amdgcn_readfirstlane(g.nt);
;     unsigned voffA[2], voffB[2];
; #pragma unroll
;     for (int i = 0; i < 2; ++i) { int R, C; stage_rc(tid * 16 + i * 8192, R, C); const int Rb = Epi::PERM ? ((R & ~31) + perm32(R & 31)) : R;
;         voffA[i] = (unsigned)(R * K + C) * 2u; voffB[i] = (unsigned)(Rb * K + C) * 2u; }
;     const size_t kstep = (size_t)(BK * 2);
;     const size_t hstep = (size_t)HALF * K * 2;
;     const size_t tstep = 2 * hstep;
;     const unsigned ldsw = (unsigned)wid * 1024u;
;     const int aoff = lds_byte(wr * 64 + fr, fq * 8), boff = lds_byte(wc * 32 + fr, fq * 8);
;     ...
;     if constexpr (SP2) {
;         PG8_STAGE(PG8_SB(0, 0), cB, voffB); PG8_STAGE(PG8_SB(0, 1), cB + hstep, voffB); PG8_STAGE(PG8_SA(0, 0), cA, voffA); PG8_STAGE(PG8_SA(0, 1), cA + hstep, voffA);
;         if (wr == 1) PG8_BAR;
;         PG8_WAIT_V(2); PG8_BAR;
;         PG8_STAGE(PG8_SB(1, 0), cB + kstep, voffB); PG8_STAGE(PG8_SA(1, 0), cA + kstep, voffA); PG8_STAGE(PG8_SB(1, 1), cB + hstep + kstep, voffB);
;         PG8_WAIT_V(6); PG8_BAR;
.LBB0_1830:
	s_lshl_b32 s10, s10, 5
	s_and_b32 s16, s10, 0x60
	s_lshl_b32 s3, s1, 13
	s_lshl_b32 s17, s16, 7
	s_add_u32 s58, s34, 0x3ab00000
	s_addc_u32 s59, s35, 0
	s_add_u32 s14, s8, 0x80080
	s_mov_b64 s[10:11], 0x80
	s_addc_u32 s15, s9, 0
	s_add_i32 m0, s54, 0x18000
	v_lshl_add_u64 v[8:9], v[8:9], 0, s[10:11]
	global_load_lds_dwordx4 v[8:9], off
	v_lshl_add_u64 v[6:7], v[6:7], 0, s[10:11]
	s_add_i32 m0, s54, 0x1a000
	s_add_i32 s60, s54, 0x8000
	global_load_lds_dwordx4 v[6:7], off
	v_lshl_add_u64 v[2:3], v[2:3], 0, s[10:11]
	s_mov_b32 m0, s60
	s_add_i32 s61, s54, 0xa000
	global_load_lds_dwordx4 v[2:3], off
	v_lshl_add_u64 v[2:3], v[4:5], 0, s[10:11]
	s_mov_b32 m0, s61
	s_mov_b32 s62, 0
	global_load_lds_dwordx4 v[2:3], off
	s_add_i32 m0, s54, 0x1c000
	v_lshl_add_u64 v[2:3], s[14:15], 0, v[132:133]
	global_load_lds_dwordx4 v[2:3], off
	v_lshl_add_u64 v[2:3], s[14:15], 0, v[130:131]
	s_add_i32 m0, s54, 0x1e000
	s_cmpk_lt_u32 s0, 0x100
	global_load_lds_dwordx4 v[2:3], off
	s_waitcnt vmcnt(8)
	s_barrier
	v_bfe_u32 v2, v10, 4, 2
	v_and_b32_e32 v3, 15, v10
	v_lshlrev_b32_e32 v5, 4, v2
	v_lshl_or_b32 v4, s1, 6, v3
	v_lshl_or_b32 v3, v3, 6, v5
	v_lshlrev_b32_e32 v5, 2, v10
	v_and_b32_e32 v5, 32, v5
	s_waitcnt vmcnt(6)
	v_bitop3_b32 v6, v3, s3, v5 bitop3:0xde
	v_bitop3_b32 v134, v3, s17, v5 bitop3:0xde
	s_cselect_b64 s[14:15], -1, 0
	s_add_i32 s63, 0, 0x10000
	s_add_i32 s64, 0, 0x14000
	v_add_u32_e32 v135, 0xffffe000, v4
	v_lshl_or_b32 v136, v2, 2, s16
	v_add_u32_e32 v137, s63, v134
	v_add_u32_e32 v138, s64, v134
	v_add_u32_e32 v139, 0, v6
	s_mov_b64 s[16:17], 0x100000
	s_mov_b32 s65, 0x100000
	s_mov_b64 s[18:19], 0x120000
	s_mov_b32 s66, 0x120000
	s_mov_b64 s[20:21], 0x140000
	s_mov_b32 s67, 0x140000
	s_mov_b64 s[22:23], 0x160000
	s_mov_b32 s68, s52
	s_mov_b32 s69, s53
	s_barrier
	s_branch .LBB0_1833
